# attention: the inter-branch and end-of-unit workgroup barriers keep lgkmcnt(0) but no longer drain vmcnt (prefetched next-block loads / output stores stay in flight across s_barrier)
# speedup vs baseline: 1.0100x; 1.0100x over previous
.LBB0_171:
	s_or_b64 exec, exec, s[24:25]
	v_ashrrev_i32_e32 v1, 3, v1
	v_lshlrev_b32_e32 v35, 1, v1
	v_lshlrev_b32_e32 v34, 7, v34
	v_and_b32_e32 v35, 8, v35
	v_bfe_u32 v39, v1, 3, 28
	v_add3_u32 v38, 0, v34, v35
	v_bitop3_b32 v34, v39, s1, 7 bitop3:0x78
	v_lshl_add_u32 v40, v34, 4, v38
	ds_read_b64 v[34:35], v40
	v_and_b32_e32 v1, 0x7ffffffc, v1
	v_add_u32_e32 v1, 32, v1
	v_lshrrev_b32_e32 v1, 3, v1
	s_add_i32 s0, 0, 0x10000
	s_waitcnt lgkmcnt(0)
	v_lshlrev_b32_e32 v36, 16, v35
	v_and_b32_e32 v37, 0xffff0000, v35
	v_pk_add_f32 v[20:21], v[20:21], v[36:37]
	v_lshlrev_b32_e32 v36, 16, v34
	v_and_b32_e32 v37, 0xffff0000, v34
	v_pk_add_f32 v[18:19], v[18:19], v[36:37]
	s_or_b32 s78, s78, s66
	v_cvt_pk_bf16_f32 v18, v18, v19
	v_cvt_pk_bf16_f32 v19, v20, v21
	ds_write_b64 v40, v[18:19]
	v_add_u32_e32 v18, 1, v39
	v_bitop3_b32 v18, v18, s1, 7 bitop3:0x78
	v_lshl_add_u32 v34, v18, 4, v38
	ds_read_b64 v[18:19], v34
	s_waitcnt lgkmcnt(0)
	v_lshlrev_b32_e32 v20, 16, v19
	v_and_b32_e32 v21, 0xffff0000, v19
	v_pk_add_f32 v[20:21], v[24:25], v[20:21]
	v_lshlrev_b32_e32 v24, 16, v18
	v_and_b32_e32 v25, 0xffff0000, v18
	v_pk_add_f32 v[18:19], v[22:23], v[24:25]
	s_nop 0
	v_cvt_pk_bf16_f32 v18, v18, v19
	v_cvt_pk_bf16_f32 v19, v20, v21
	ds_write_b64 v34, v[18:19]
	v_add_u32_e32 v18, 2, v39
	v_bitop3_b32 v18, v18, s1, 7 bitop3:0x78
	v_lshl_add_u32 v24, v18, 4, v38
	ds_read_b64 v[18:19], v24
	s_waitcnt lgkmcnt(0)
	v_lshlrev_b32_e32 v20, 16, v19
	v_and_b32_e32 v21, 0xffff0000, v19
	v_lshlrev_b32_e32 v22, 16, v18
	v_and_b32_e32 v23, 0xffff0000, v18
	v_pk_add_f32 v[20:21], v[28:29], v[20:21]
	v_pk_add_f32 v[18:19], v[26:27], v[22:23]
	s_nop 0
	v_cvt_pk_bf16_f32 v18, v18, v19
	v_cvt_pk_bf16_f32 v19, v20, v21
	ds_write_b64 v24, v[18:19]
	v_add_u32_e32 v18, 3, v39
	v_bitop3_b32 v18, v18, s1, 7 bitop3:0x78
	v_lshl_add_u32 v24, v18, 4, v38
	ds_read_b64 v[18:19], v24
	s_waitcnt lgkmcnt(0)
	v_lshlrev_b32_e32 v20, 16, v19
	v_and_b32_e32 v21, 0xffff0000, v19
	v_lshlrev_b32_e32 v22, 16, v18
	v_and_b32_e32 v23, 0xffff0000, v18
	v_pk_add_f32 v[20:21], v[32:33], v[20:21]
	v_pk_add_f32 v[18:19], v[30:31], v[22:23]
	s_nop 0
	v_cvt_pk_bf16_f32 v18, v18, v19
	v_cvt_pk_bf16_f32 v19, v20, v21
	ds_write_b64 v24, v[18:19]
	v_bitop3_b32 v18, v1, s1, 7 bitop3:0x78
	v_lshl_add_u32 v22, v18, 4, v38
	ds_read_b64 v[18:19], v22
	s_waitcnt lgkmcnt(0)
	v_lshlrev_b32_e32 v20, 16, v19
	v_and_b32_e32 v21, 0xffff0000, v19
	v_pk_add_f32 v[4:5], v[4:5], v[20:21]
	v_lshlrev_b32_e32 v20, 16, v18
	v_and_b32_e32 v21, 0xffff0000, v18
	v_pk_add_f32 v[2:3], v[2:3], v[20:21]
	s_nop 0
	v_cvt_pk_bf16_f32 v2, v2, v3
	v_cvt_pk_bf16_f32 v3, v4, v5
	ds_write_b64 v22, v[2:3]
	v_add_u32_e32 v2, 1, v1
	v_bitop3_b32 v2, v2, s1, 7 bitop3:0x78
	v_lshl_add_u32 v18, v2, 4, v38
	ds_read_b64 v[2:3], v18
	s_waitcnt lgkmcnt(0)
	v_lshlrev_b32_e32 v4, 16, v3
	v_and_b32_e32 v5, 0xffff0000, v3
	v_pk_add_f32 v[4:5], v[8:9], v[4:5]
	v_lshlrev_b32_e32 v8, 16, v2
	v_and_b32_e32 v9, 0xffff0000, v2
	v_pk_add_f32 v[2:3], v[6:7], v[8:9]
	s_nop 0
	v_cvt_pk_bf16_f32 v2, v2, v3
	v_cvt_pk_bf16_f32 v3, v4, v5
	ds_write_b64 v18, v[2:3]
	v_add_u32_e32 v2, 2, v1
	v_bitop3_b32 v2, v2, s1, 7 bitop3:0x78
	v_lshl_add_u32 v8, v2, 4, v38
	ds_read_b64 v[2:3], v8
	v_add_u32_e32 v1, 3, v1
	v_bitop3_b32 v1, v1, s1, 7 bitop3:0x78
	v_lshl_add_u32 v1, v1, 4, v38
	s_waitcnt lgkmcnt(0)
	v_lshlrev_b32_e32 v4, 16, v3
	v_and_b32_e32 v5, 0xffff0000, v3
	v_lshlrev_b32_e32 v6, 16, v2
	v_and_b32_e32 v7, 0xffff0000, v2
	v_pk_add_f32 v[4:5], v[12:13], v[4:5]
	v_pk_add_f32 v[2:3], v[10:11], v[6:7]
	s_nop 0
	v_cvt_pk_bf16_f32 v2, v2, v3
	v_cvt_pk_bf16_f32 v3, v4, v5
	ds_write_b64 v8, v[2:3]
	ds_read_b64 v[2:3], v1
	s_waitcnt lgkmcnt(0)
	v_lshlrev_b32_e32 v4, 16, v3
	v_and_b32_e32 v5, 0xffff0000, v3
	v_lshlrev_b32_e32 v6, 16, v2
	v_and_b32_e32 v7, 0xffff0000, v2
	v_pk_add_f32 v[4:5], v[16:17], v[4:5]
	v_pk_add_f32 v[2:3], v[14:15], v[6:7]
	s_nop 0
	v_cvt_pk_bf16_f32 v2, v2, v3
	v_cvt_pk_bf16_f32 v3, v4, v5
	ds_write_b64 v1, v[2:3]
	v_mov_b32_e32 v1, v228
	s_waitcnt vmcnt(0) lgkmcnt(0)
	s_barrier
	s_nop 0
	v_add_u32_e32 v17, s54, v1
	v_ashrrev_i32_e32 v12, 3, v17
	v_xor_b32_e32 v3, v12, v1
	v_lshlrev_b32_e32 v3, 4, v3
	v_lshlrev_b32_e32 v2, 7, v12
	v_and_b32_e32 v3, 0x70, v3
	v_add3_u32 v2, 0, v2, v3
	v_lshl_add_u32 v3, v12, 2, s0
	ds_read_b128 v[4:7], v2
	ds_read_b32 v8, v3
	v_lshlrev_b32_e32 v2, 4, v1
	v_and_b32_e32 v2, 0x70, v2
	v_mov_b32_e32 v3, v0
	s_waitcnt lgkmcnt(1)
	v_lshlrev_b32_e32 v10, 16, v4
	s_waitcnt lgkmcnt(0)
	v_rcp_f32_e32 v8, v8
	v_and_b32_e32 v11, 0xffff0000, v4
	v_lshl_add_u64 v[2:3], s[82:83], 0, v[2:3]
	v_pk_mul_f32 v[10:11], v[8:9], v[10:11] op_sel_hi:[0,1]
	v_cvt_pk_bf16_f32 v4, v10, v11
	v_lshlrev_b32_e32 v10, 16, v5
	v_and_b32_e32 v11, 0xffff0000, v5
	v_pk_mul_f32 v[10:11], v[8:9], v[10:11] op_sel_hi:[0,1]
	v_cvt_pk_bf16_f32 v5, v10, v11
	v_lshlrev_b32_e32 v10, 16, v6
	v_and_b32_e32 v11, 0xffff0000, v6
	v_pk_mul_f32 v[10:11], v[8:9], v[10:11] op_sel_hi:[0,1]
	v_cvt_pk_bf16_f32 v6, v10, v11
	v_lshlrev_b32_e32 v10, 16, v7
	v_and_b32_e32 v11, 0xffff0000, v7
	v_pk_mul_f32 v[8:9], v[8:9], v[10:11] op_sel_hi:[0,1]
	v_cvt_pk_bf16_f32 v7, v8, v9
	v_add_u32_e32 v8, 0x200, v17
	v_ashrrev_i32_e32 v14, 3, v8
	v_xor_b32_e32 v9, v14, v1
	v_lshlrev_b32_e32 v9, 4, v9
	v_lshlrev_b32_e32 v8, 7, v14
	v_and_b32_e32 v9, 0x70, v9
	v_add3_u32 v8, 0, v8, v9
	v_lshl_add_u32 v13, v14, 2, s0
	ds_read_b128 v[8:11], v8
	ds_read_b32 v15, v13
	v_ashrrev_i32_e32 v13, 31, v12
	v_lshl_add_u64 v[12:13], s[78:79], 0, v[12:13]
	v_lshlrev_b64 v[12:13], 11, v[12:13]
	v_lshl_add_u64 v[12:13], v[2:3], 0, v[12:13]
	s_waitcnt lgkmcnt(0)
	v_rcp_f32_e32 v16, v15
	global_store_dwordx4 v[12:13], v[4:7], off
	v_ashrrev_i32_e32 v15, 31, v14
	v_lshl_add_u64 v[14:15], s[78:79], 0, v[14:15]
	v_lshlrev_b32_e32 v4, 16, v8
	v_and_b32_e32 v5, 0xffff0000, v8
	v_lshlrev_b32_e32 v6, 16, v9
	v_and_b32_e32 v7, 0xffff0000, v9
	v_pk_mul_f32 v[4:5], v[16:17], v[4:5] op_sel_hi:[0,1]
	v_pk_mul_f32 v[6:7], v[16:17], v[6:7] op_sel_hi:[0,1]
	v_cvt_pk_bf16_f32 v4, v4, v5
	v_cvt_pk_bf16_f32 v5, v6, v7
	v_lshlrev_b32_e32 v6, 16, v10
	v_and_b32_e32 v7, 0xffff0000, v10
	v_lshlrev_b32_e32 v8, 16, v11
	v_and_b32_e32 v9, 0xffff0000, v11
	v_pk_mul_f32 v[6:7], v[16:17], v[6:7] op_sel_hi:[0,1]
	v_pk_mul_f32 v[8:9], v[16:17], v[8:9] op_sel_hi:[0,1]
	v_cvt_pk_bf16_f32 v6, v6, v7
	v_cvt_pk_bf16_f32 v7, v8, v9
	v_add_u32_e32 v8, 0x400, v17
	v_ashrrev_i32_e32 v12, 3, v8
	v_xor_b32_e32 v9, v12, v1
	v_lshlrev_b32_e32 v9, 4, v9
	v_lshlrev_b32_e32 v8, 7, v12
	v_and_b32_e32 v9, 0x70, v9
	v_add3_u32 v8, 0, v8, v9
	v_lshl_add_u32 v13, v12, 2, s0
	ds_read_b128 v[8:11], v8
	ds_read_b32 v13, v13
	v_lshlrev_b64 v[14:15], 11, v[14:15]
	v_lshl_add_u64 v[14:15], v[2:3], 0, v[14:15]
	global_store_dwordx4 v[14:15], v[4:7], off
	s_waitcnt lgkmcnt(0)
	v_rcp_f32_e32 v16, v13
	v_lshlrev_b32_e32 v4, 16, v8
	v_and_b32_e32 v5, 0xffff0000, v8
	v_lshlrev_b32_e32 v6, 16, v9
	v_and_b32_e32 v7, 0xffff0000, v9
	v_pk_mul_f32 v[4:5], v[16:17], v[4:5] op_sel_hi:[0,1]
	v_pk_mul_f32 v[6:7], v[16:17], v[6:7] op_sel_hi:[0,1]
	v_cvt_pk_bf16_f32 v4, v4, v5
	v_cvt_pk_bf16_f32 v5, v6, v7
	v_lshlrev_b32_e32 v6, 16, v10
	v_and_b32_e32 v7, 0xffff0000, v10
	v_lshlrev_b32_e32 v8, 16, v11
	v_and_b32_e32 v9, 0xffff0000, v11
	v_pk_mul_f32 v[6:7], v[16:17], v[6:7] op_sel_hi:[0,1]
	v_pk_mul_f32 v[8:9], v[16:17], v[8:9] op_sel_hi:[0,1]
	v_cvt_pk_bf16_f32 v6, v6, v7
	v_cvt_pk_bf16_f32 v7, v8, v9
	v_add_u32_e32 v8, 0x600, v17
	v_ashrrev_i32_e32 v14, 3, v8
	v_xor_b32_e32 v9, v14, v1
	v_lshlrev_b32_e32 v9, 4, v9
	v_lshlrev_b32_e32 v8, 7, v14
	v_and_b32_e32 v9, 0x70, v9
	v_add3_u32 v8, 0, v8, v9
	v_lshl_add_u32 v13, v14, 2, s0
	ds_read_b128 v[8:11], v8
	ds_read_b32 v15, v13
	v_ashrrev_i32_e32 v13, 31, v12
	v_lshl_add_u64 v[12:13], s[78:79], 0, v[12:13]
	v_lshlrev_b64 v[12:13], 11, v[12:13]
	v_lshl_add_u64 v[12:13], v[2:3], 0, v[12:13]
	s_waitcnt lgkmcnt(0)
	v_rcp_f32_e32 v16, v15
	global_store_dwordx4 v[12:13], v[4:7], off
	v_ashrrev_i32_e32 v15, 31, v14
	v_lshl_add_u64 v[14:15], s[78:79], 0, v[14:15]
	v_lshlrev_b32_e32 v4, 16, v8
	v_and_b32_e32 v5, 0xffff0000, v8
	v_lshlrev_b32_e32 v6, 16, v9
	v_and_b32_e32 v7, 0xffff0000, v9
	v_pk_mul_f32 v[4:5], v[16:17], v[4:5] op_sel_hi:[0,1]
	v_pk_mul_f32 v[6:7], v[16:17], v[6:7] op_sel_hi:[0,1]
	v_cvt_pk_bf16_f32 v4, v4, v5
	v_cvt_pk_bf16_f32 v5, v6, v7
	v_lshlrev_b32_e32 v6, 16, v10
	v_and_b32_e32 v7, 0xffff0000, v10
	v_lshlrev_b32_e32 v8, 16, v11
	v_and_b32_e32 v9, 0xffff0000, v11
	v_pk_mul_f32 v[6:7], v[16:17], v[6:7] op_sel_hi:[0,1]
	v_pk_mul_f32 v[8:9], v[16:17], v[8:9] op_sel_hi:[0,1]
	v_cvt_pk_bf16_f32 v6, v6, v7
	v_cvt_pk_bf16_f32 v7, v8, v9
	v_add_u32_e32 v8, 0x800, v17
	v_ashrrev_i32_e32 v12, 3, v8
	v_xor_b32_e32 v9, v12, v1
	v_lshlrev_b32_e32 v9, 4, v9
	v_lshlrev_b32_e32 v8, 7, v12
	v_and_b32_e32 v9, 0x70, v9
	v_add3_u32 v8, 0, v8, v9
	v_lshl_add_u32 v13, v12, 2, s0
	ds_read_b128 v[8:11], v8
	ds_read_b32 v13, v13
	v_lshlrev_b64 v[14:15], 11, v[14:15]
	v_lshl_add_u64 v[14:15], v[2:3], 0, v[14:15]
	global_store_dwordx4 v[14:15], v[4:7], off
	s_waitcnt lgkmcnt(0)
	v_rcp_f32_e32 v16, v13
	v_lshlrev_b32_e32 v4, 16, v8
	v_and_b32_e32 v5, 0xffff0000, v8
	v_lshlrev_b32_e32 v6, 16, v9
	v_and_b32_e32 v7, 0xffff0000, v9
	v_pk_mul_f32 v[4:5], v[16:17], v[4:5] op_sel_hi:[0,1]
	v_pk_mul_f32 v[6:7], v[16:17], v[6:7] op_sel_hi:[0,1]
	v_cvt_pk_bf16_f32 v4, v4, v5
	v_cvt_pk_bf16_f32 v5, v6, v7
	v_lshlrev_b32_e32 v6, 16, v10
	v_and_b32_e32 v7, 0xffff0000, v10
	v_lshlrev_b32_e32 v8, 16, v11
	v_and_b32_e32 v9, 0xffff0000, v11
	v_pk_mul_f32 v[6:7], v[16:17], v[6:7] op_sel_hi:[0,1]
	v_pk_mul_f32 v[8:9], v[16:17], v[8:9] op_sel_hi:[0,1]
	v_cvt_pk_bf16_f32 v6, v6, v7
	v_cvt_pk_bf16_f32 v7, v8, v9
	v_add_u32_e32 v8, 0xa00, v17
	v_ashrrev_i32_e32 v14, 3, v8
	v_xor_b32_e32 v9, v14, v1
	v_lshlrev_b32_e32 v9, 4, v9
	v_lshlrev_b32_e32 v8, 7, v14
	v_and_b32_e32 v9, 0x70, v9
	v_add3_u32 v8, 0, v8, v9
	v_lshl_add_u32 v13, v14, 2, s0
	ds_read_b128 v[8:11], v8
	ds_read_b32 v15, v13
	v_ashrrev_i32_e32 v13, 31, v12
	v_lshl_add_u64 v[12:13], s[78:79], 0, v[12:13]
	v_lshlrev_b64 v[12:13], 11, v[12:13]
	v_lshl_add_u64 v[12:13], v[2:3], 0, v[12:13]
	s_waitcnt lgkmcnt(0)
	v_rcp_f32_e32 v16, v15
	global_store_dwordx4 v[12:13], v[4:7], off
	v_ashrrev_i32_e32 v15, 31, v14
	v_lshl_add_u64 v[14:15], s[78:79], 0, v[14:15]
	v_lshlrev_b32_e32 v4, 16, v8
	v_and_b32_e32 v5, 0xffff0000, v8
	v_lshlrev_b32_e32 v6, 16, v9
	v_and_b32_e32 v7, 0xffff0000, v9
	v_pk_mul_f32 v[4:5], v[16:17], v[4:5] op_sel_hi:[0,1]
	v_pk_mul_f32 v[6:7], v[16:17], v[6:7] op_sel_hi:[0,1]
	v_cvt_pk_bf16_f32 v4, v4, v5
	v_cvt_pk_bf16_f32 v5, v6, v7
	v_lshlrev_b32_e32 v6, 16, v10
	v_and_b32_e32 v7, 0xffff0000, v10
	v_lshlrev_b32_e32 v8, 16, v11
	v_and_b32_e32 v9, 0xffff0000, v11
	v_pk_mul_f32 v[6:7], v[16:17], v[6:7] op_sel_hi:[0,1]
	v_pk_mul_f32 v[8:9], v[16:17], v[8:9] op_sel_hi:[0,1]
	v_cvt_pk_bf16_f32 v6, v6, v7
	v_cvt_pk_bf16_f32 v7, v8, v9
	v_add_u32_e32 v8, 0xc00, v17
	v_ashrrev_i32_e32 v12, 3, v8
	v_xor_b32_e32 v9, v12, v1
	v_lshlrev_b32_e32 v9, 4, v9
	v_lshlrev_b32_e32 v8, 7, v12
	v_and_b32_e32 v9, 0x70, v9
	v_add3_u32 v8, 0, v8, v9
	v_lshl_add_u32 v13, v12, 2, s0
	ds_read_b128 v[8:11], v8
	ds_read_b32 v13, v13
	v_lshlrev_b64 v[14:15], 11, v[14:15]
	v_lshl_add_u64 v[14:15], v[2:3], 0, v[14:15]
	global_store_dwordx4 v[14:15], v[4:7], off
	s_waitcnt lgkmcnt(0)
	v_rcp_f32_e32 v16, v13
	v_lshlrev_b32_e32 v4, 16, v8
	v_and_b32_e32 v5, 0xffff0000, v8
	v_lshlrev_b32_e32 v6, 16, v9
	v_and_b32_e32 v7, 0xffff0000, v9
	v_pk_mul_f32 v[4:5], v[16:17], v[4:5] op_sel_hi:[0,1]
	v_pk_mul_f32 v[6:7], v[16:17], v[6:7] op_sel_hi:[0,1]
	v_cvt_pk_bf16_f32 v4, v4, v5
	v_cvt_pk_bf16_f32 v5, v6, v7
	v_lshlrev_b32_e32 v6, 16, v10
	v_and_b32_e32 v7, 0xffff0000, v10
	v_lshlrev_b32_e32 v8, 16, v11
	v_and_b32_e32 v9, 0xffff0000, v11
	v_pk_mul_f32 v[6:7], v[16:17], v[6:7] op_sel_hi:[0,1]
	v_pk_mul_f32 v[8:9], v[16:17], v[8:9] op_sel_hi:[0,1]
	v_cvt_pk_bf16_f32 v6, v6, v7
	v_cvt_pk_bf16_f32 v7, v8, v9
	v_add_u32_e32 v8, 0xe00, v17
	v_ashrrev_i32_e32 v14, 3, v8
	v_xor_b32_e32 v1, v14, v1
	v_lshlrev_b32_e32 v1, 4, v1
	v_lshlrev_b32_e32 v8, 7, v14
	v_and_b32_e32 v1, 0x70, v1
	v_add3_u32 v1, 0, v8, v1
	v_lshl_add_u32 v13, v14, 2, s0
	ds_read_b128 v[8:11], v1
	ds_read_b32 v1, v13
	v_ashrrev_i32_e32 v13, 31, v12
	v_lshl_add_u64 v[12:13], s[78:79], 0, v[12:13]
	v_lshlrev_b64 v[12:13], 11, v[12:13]
	v_lshl_add_u64 v[12:13], v[2:3], 0, v[12:13]
	s_waitcnt lgkmcnt(0)
	v_rcp_f32_e32 v16, v1
	global_store_dwordx4 v[12:13], v[4:7], off
	v_ashrrev_i32_e32 v15, 31, v14
	v_readlane_b32 s0, v252, 26
	v_lshlrev_b32_e32 v4, 16, v8
	v_and_b32_e32 v5, 0xffff0000, v8
	v_lshlrev_b32_e32 v6, 16, v9
	v_and_b32_e32 v7, 0xffff0000, v9
	v_pk_mul_f32 v[4:5], v[16:17], v[4:5] op_sel_hi:[0,1]
	v_pk_mul_f32 v[6:7], v[16:17], v[6:7] op_sel_hi:[0,1]
	v_cvt_pk_bf16_f32 v4, v4, v5
	v_cvt_pk_bf16_f32 v5, v6, v7
	v_lshlrev_b32_e32 v6, 16, v10
	v_and_b32_e32 v7, 0xffff0000, v10
	v_lshlrev_b32_e32 v8, 16, v11
	v_and_b32_e32 v9, 0xffff0000, v11
	v_pk_mul_f32 v[6:7], v[16:17], v[6:7] op_sel_hi:[0,1]
	v_pk_mul_f32 v[8:9], v[16:17], v[8:9] op_sel_hi:[0,1]
	v_cvt_pk_bf16_f32 v6, v6, v7
	v_cvt_pk_bf16_f32 v7, v8, v9
	v_lshl_add_u64 v[8:9], s[78:79], 0, v[14:15]
	v_lshlrev_b64 v[8:9], 11, v[8:9]
	v_lshl_add_u64 v[2:3], v[2:3], 0, v[8:9]
	global_store_dwordx4 v[2:3], v[4:7], off
	s_waitcnt lgkmcnt(0)
	s_barrier
	s_add_i32 s63, s0, s63
	v_readlane_b32 s0, v253, 53
	s_add_i32 s62, s62, s0
	s_cmpk_gt_i32 s63, 0xff
	s_cbranch_scc1 .LBB0_312

.LBB0_217:
	s_or_b64 exec, exec, s[24:25]
	v_lshl_add_u32 v1, v1, 7, v68
	s_waitcnt lgkmcnt(1)
	v_add_u32_e32 v37, v1, v69
	v_cvt_pk_bf16_f32 v18, v18, v19
	v_cvt_pk_bf16_f32 v19, v20, v21
	ds_write_b64 v37, v[18:19]
	v_add_u32_e32 v20, v1, v50
	v_cvt_pk_bf16_f32 v18, v22, v23
	v_cvt_pk_bf16_f32 v19, v24, v25
	ds_write_b64 v20, v[18:19]
	v_add_u32_e32 v20, v1, v51
	v_cvt_pk_bf16_f32 v18, v26, v27
	v_cvt_pk_bf16_f32 v19, v28, v29
	ds_write_b64 v20, v[18:19]
	v_add_u32_e32 v20, v1, v52
	v_cvt_pk_bf16_f32 v18, v30, v31
	v_cvt_pk_bf16_f32 v19, v32, v33
	ds_write_b64 v20, v[18:19]
	v_add_u32_e32 v18, v1, v53
	v_cvt_pk_bf16_f32 v2, v2, v3
	v_cvt_pk_bf16_f32 v3, v4, v5
	ds_write_b64 v18, v[2:3]
	v_add_u32_e32 v4, v1, v34
	v_cvt_pk_bf16_f32 v2, v6, v7
	v_cvt_pk_bf16_f32 v3, v8, v9
	ds_write_b64 v4, v[2:3]
	v_add_u32_e32 v4, v1, v35
	v_cvt_pk_bf16_f32 v2, v10, v11
	v_cvt_pk_bf16_f32 v3, v12, v13
	s_sub_i32 s24, 0xfff, s1
	ds_write_b64 v4, v[2:3]
	v_add_u32_e32 v1, v1, v36
	v_cvt_pk_bf16_f32 v2, v14, v15
	v_cvt_pk_bf16_f32 v3, v16, v17
	s_ashr_i32 s26, s24, 31
	ds_write_b64 v1, v[2:3]
	v_mov_b32_e32 v192, v228
	s_lshr_b32 s26, s26, 30
	s_waitcnt lgkmcnt(0)
	s_barrier
	s_add_i32 s24, s24, s26
	v_and_b32_e32 v216, 31, v192
	v_mov_b32_e32 v5, s49
	v_ashrrev_i32_e32 v1, 5, v192
	s_ashr_i32 s28, s24, 2
	v_ashrrev_i32_e32 v4, 3, v192
	v_lshlrev_b32_e32 v2, 4, v192
	v_mad_u32_u24 v17, v216, s64, v5
	v_and_b32_e32 v5, 16, v192
	v_bfe_u32 v6, v192, 2, 2
	s_mov_b32 s24, 0xffffffc
	v_lshlrev_b32_e32 v7, 2, v192
	v_and_b32_e32 v2, 0x70, v2
	v_mov_b32_e32 v3, v0
	v_lshlrev_b32_e32 v18, 4, v1
	v_and_or_b32 v6, v4, s24, v6
	v_and_or_b32 v5, v7, 12, v5
	v_lshlrev_b32_e32 v215, 2, v1
	v_ashrrev_i32_e32 v1, 1, v192
	s_lshr_b32 s0, s42, 30
	v_add_u32_e32 v16, s49, v2
	v_lshl_add_u64 v[184:185], s[72:73], 0, v[2:3]
	v_mul_lo_u32 v19, v4, s64
	v_and_b32_e32 v1, -4, v1
	v_mul_lo_u32 v20, v6, s64
	v_lshl_add_u32 v21, v5, 1, s49
	v_lshl_add_u64 v[190:191], s[82:83], 0, v[2:3]
	v_sub_u32_e32 v2, v216, v215
	s_add_i32 s24, s59, s67
	v_mov_b32_e32 v14, v0
	v_mov_b32_e32 v15, v0
	v_mul_f32_e32 v178, 4.0, v214
	s_add_i32 s0, s1, s0
	v_add_u32_e32 v219, 64, v2
	v_add_u32_e32 v229, s24, v1
	v_mov_b32_e32 v1, v0
	v_mov_b32_e32 v2, v0
	v_mov_b32_e32 v4, v0
	v_mov_b32_e32 v5, v0
	v_mov_b32_e32 v6, v0
	v_mov_b32_e32 v7, v0
	v_mov_b32_e32 v8, v0
	v_mov_b32_e32 v9, v0
	v_mov_b32_e32 v10, v0
	v_mov_b32_e32 v11, v0
	v_mov_b32_e32 v12, v0
	v_mov_b32_e32 v13, v0
	v_add_u32_e32 v230, v16, v19
	v_add_u32_e32 v218, v17, v18
	v_add_u32_e32 v217, v21, v20
	v_mov_b64_e32 v[32:33], v[14:15]
	s_ashr_i32 s25, s0, 2
	v_xor_b32_e32 v186, 0x80000000, v178
	v_mov_b32_e32 v193, 0
	v_mov_b64_e32 v[30:31], v[12:13]
	v_mov_b64_e32 v[28:29], v[10:11]
	v_mov_b64_e32 v[26:27], v[8:9]
	v_mov_b64_e32 v[24:25], v[6:7]
	v_mov_b64_e32 v[22:23], v[4:5]
	v_mov_b64_e32 v[20:21], v[2:3]
	v_mov_b64_e32 v[18:19], v[0:1]
	v_mov_b64_e32 v[16:17], v[14:15]
	s_mov_b32 s0, 0
	s_sub_i32 s3, 0, s25
	s_sub_i32 s29, 64, s25
	s_add_i32 s42, s28, 33
	v_mov_b32_e32 v179, v178
	v_mov_b32_e32 v182, v186
	v_mov_b32_e32 v183, v186
	v_mov_b32_e32 v188, v186
	v_mov_b32_e32 v189, v186
	v_mov_b32_e32 v181, 0
	v_mov_b64_e32 v[14:15], v[12:13]
	v_mov_b64_e32 v[12:13], v[10:11]
	v_mov_b64_e32 v[10:11], v[8:9]
	v_mov_b64_e32 v[8:9], v[6:7]
	v_mov_b64_e32 v[6:7], v[4:5]
	v_mov_b64_e32 v[4:5], v[2:3]
	v_mov_b64_e32 v[2:3], v[0:1]
	v_mov_b32_e32 v50, 0
	v_mov_b32_e32 v51, v193
	v_mov_b32_e32 v52, v193
	v_mov_b32_e32 v53, v193
	v_mov_b32_e32 v54, v193
	v_mov_b32_e32 v55, v193
	v_mov_b32_e32 v56, v193
	v_mov_b32_e32 v57, v193
	v_mov_b32_e32 v58, v193
	v_mov_b32_e32 v59, v193
	v_mov_b32_e32 v60, v193
	v_mov_b32_e32 v61, v193
	v_mov_b32_e32 v62, v193
	v_mov_b32_e32 v63, v193
	v_mov_b32_e32 v64, v193
	v_mov_b32_e32 v65, v193
	v_mov_b32_e32 v34, 0
	v_mov_b32_e32 v35, v193
	v_mov_b32_e32 v36, v193
	v_mov_b32_e32 v37, v193
	v_mov_b32_e32 v38, v193
	v_mov_b32_e32 v39, v193
	v_mov_b32_e32 v40, v193
	v_mov_b32_e32 v41, v193
	v_mov_b32_e32 v42, v193
	v_mov_b32_e32 v43, v193
	v_mov_b32_e32 v44, v193
	v_mov_b32_e32 v45, v193
	v_mov_b32_e32 v46, v193
	v_mov_b32_e32 v47, v193
	v_mov_b32_e32 v48, v193
	v_mov_b32_e32 v49, v193
	s_branch .LBB0_220

.LBB0_262:
	s_or_b64 exec, exec, s[24:25]
	v_lshl_add_u32 v37, v37, 7, v69
	v_add_u32_e32 v44, v37, v70
	s_waitcnt lgkmcnt(0)
	ds_read_b64 v[38:39], v44
	v_add_u32_e32 v1, v37, v1
	s_sub_i32 s24, 0xfff, s0
	s_ashr_i32 s26, s24, 31
	s_lshr_b32 s26, s26, 28
	s_waitcnt lgkmcnt(0)
	v_lshlrev_b32_e32 v40, 16, v39
	v_and_b32_e32 v41, 0xffff0000, v39
	v_lshlrev_b32_e32 v42, 16, v38
	v_and_b32_e32 v43, 0xffff0000, v38
	v_pk_add_f32 v[20:21], v[20:21], v[40:41]
	v_pk_add_f32 v[18:19], v[18:19], v[42:43]
	v_add_u32_e32 v40, v37, v50
	v_cvt_pk_bf16_f32 v18, v18, v19
	v_cvt_pk_bf16_f32 v19, v20, v21
	ds_write_b64 v44, v[18:19]
	ds_read_b64 v[18:19], v40
	s_add_i32 s24, s24, s26
	s_lshr_b32 s1, s29, 28
	s_ashr_i32 s28, s24, 4
	s_mov_b32 s24, 0xffffffc
	s_waitcnt lgkmcnt(0)
	v_lshlrev_b32_e32 v20, 16, v19
	v_and_b32_e32 v21, 0xffff0000, v19
	v_lshlrev_b32_e32 v38, 16, v18
	v_and_b32_e32 v39, 0xffff0000, v18
	v_pk_add_f32 v[20:21], v[24:25], v[20:21]
	v_pk_add_f32 v[18:19], v[22:23], v[38:39]
	v_add_u32_e32 v24, v37, v51
	v_cvt_pk_bf16_f32 v18, v18, v19
	v_cvt_pk_bf16_f32 v19, v20, v21
	ds_write_b64 v40, v[18:19]
	ds_read_b64 v[18:19], v24
	v_mul_f32_e32 v146, 0x41800000, v214
	s_add_i32 s1, s0, s1
	s_ashr_i32 s25, s1, 4
	v_xor_b32_e32 v150, 0x80000000, v146
	s_waitcnt lgkmcnt(0)
	v_lshlrev_b32_e32 v20, 16, v19
	v_and_b32_e32 v21, 0xffff0000, v19
	v_lshlrev_b32_e32 v22, 16, v18
	v_and_b32_e32 v23, 0xffff0000, v18
	v_pk_add_f32 v[20:21], v[28:29], v[20:21]
	v_pk_add_f32 v[18:19], v[26:27], v[22:23]
	v_mov_b32_e32 v155, 0
	v_cvt_pk_bf16_f32 v18, v18, v19
	v_cvt_pk_bf16_f32 v19, v20, v21
	ds_write_b64 v24, v[18:19]
	v_add_u32_e32 v24, v37, v52
	ds_read_b64 v[18:19], v24
	s_mov_b32 s1, 0
	s_sub_i32 s3, 0, s25
	s_sub_i32 s29, 64, s25
	s_add_i32 s30, s28, 33
	s_waitcnt lgkmcnt(0)
	v_lshlrev_b32_e32 v20, 16, v19
	v_and_b32_e32 v21, 0xffff0000, v19
	v_lshlrev_b32_e32 v22, 16, v18
	v_and_b32_e32 v23, 0xffff0000, v18
	v_pk_add_f32 v[20:21], v[32:33], v[20:21]
	v_pk_add_f32 v[18:19], v[30:31], v[22:23]
	v_mov_b32_e32 v147, v146
	v_cvt_pk_bf16_f32 v18, v18, v19
	v_cvt_pk_bf16_f32 v19, v20, v21
	ds_write_b64 v24, v[18:19]
	ds_read_b64 v[18:19], v1
	v_mov_b32_e32 v148, v150
	v_mov_b32_e32 v149, v150
	v_mov_b32_e32 v152, v150
	v_mov_b32_e32 v153, v150
	s_waitcnt lgkmcnt(0)
	v_lshlrev_b32_e32 v20, 16, v19
	v_and_b32_e32 v21, 0xffff0000, v19
	v_pk_add_f32 v[4:5], v[4:5], v[20:21]
	v_lshlrev_b32_e32 v20, 16, v18
	v_and_b32_e32 v21, 0xffff0000, v18
	v_pk_add_f32 v[2:3], v[2:3], v[20:21]
	v_mov_b32_e32 v18, v155
	v_cvt_pk_bf16_f32 v2, v2, v3
	v_cvt_pk_bf16_f32 v3, v4, v5
	ds_write_b64 v1, v[2:3]
	v_add_u32_e32 v1, v37, v34
	ds_read_b64 v[2:3], v1
	v_mov_b32_e32 v19, v155
	v_mov_b32_e32 v20, v155
	v_mov_b32_e32 v21, v155
	v_mov_b32_e32 v22, v155
	s_waitcnt lgkmcnt(0)
	v_lshlrev_b32_e32 v4, 16, v3
	v_and_b32_e32 v5, 0xffff0000, v3
	v_pk_add_f32 v[4:5], v[8:9], v[4:5]
	v_lshlrev_b32_e32 v8, 16, v2
	v_and_b32_e32 v9, 0xffff0000, v2
	v_pk_add_f32 v[2:3], v[6:7], v[8:9]
	v_mov_b32_e32 v23, v155
	v_cvt_pk_bf16_f32 v2, v2, v3
	v_cvt_pk_bf16_f32 v3, v4, v5
	ds_write_b64 v1, v[2:3]
	v_add_u32_e32 v1, v37, v35
	ds_read_b64 v[2:3], v1
	v_mov_b32_e32 v24, v155
	v_mov_b32_e32 v25, v155
	v_mov_b32_e32 v26, v155
	v_mov_b32_e32 v27, v155
	s_waitcnt lgkmcnt(0)
	v_lshlrev_b32_e32 v4, 16, v3
	v_and_b32_e32 v5, 0xffff0000, v3
	v_lshlrev_b32_e32 v6, 16, v2
	v_and_b32_e32 v7, 0xffff0000, v2
	v_pk_add_f32 v[4:5], v[12:13], v[4:5]
	v_pk_add_f32 v[2:3], v[10:11], v[6:7]
	v_mov_b32_e32 v28, v155
	v_cvt_pk_bf16_f32 v2, v2, v3
	v_cvt_pk_bf16_f32 v3, v4, v5
	ds_write_b64 v1, v[2:3]
	v_add_u32_e32 v1, v37, v36
	ds_read_b64 v[2:3], v1
	v_mov_b32_e32 v29, v155
	v_mov_b32_e32 v30, v155
	v_mov_b32_e32 v31, v155
	v_mov_b32_e32 v32, v155
	s_waitcnt lgkmcnt(0)
	v_lshlrev_b32_e32 v4, 16, v3
	v_and_b32_e32 v5, 0xffff0000, v3
	v_lshlrev_b32_e32 v6, 16, v2
	v_and_b32_e32 v7, 0xffff0000, v2
	v_pk_add_f32 v[4:5], v[16:17], v[4:5]
	v_pk_add_f32 v[2:3], v[14:15], v[6:7]
	v_mov_b32_e32 v7, s49
	v_cvt_pk_bf16_f32 v2, v2, v3
	v_cvt_pk_bf16_f32 v3, v4, v5
	ds_write_b64 v1, v[2:3]
	v_mov_b32_e32 v1, v228
	s_waitcnt lgkmcnt(0)
	s_barrier
	v_mov_b32_e32 v3, v0
	v_ashrrev_i32_e32 v4, 5, v1
	v_ashrrev_i32_e32 v5, 3, v1
	v_lshlrev_b32_e32 v2, 4, v1
	v_and_b32_e32 v9, 16, v1
	v_bfe_u32 v10, v1, 2, 2
	v_lshlrev_b32_e32 v11, 2, v1
	v_and_b32_e32 v157, 31, v1
	v_and_b32_e32 v2, 0x70, v2
	v_lshlrev_b32_e32 v8, 4, v4
	v_and_or_b32 v10, v5, s24, v10
	v_and_or_b32 v9, v11, 12, v9
	v_lshlrev_b32_e32 v156, 2, v4
	v_mul_lo_u32 v4, v5, s64
	v_lshlrev_b32_e32 v5, 1, v1
	v_add_u32_e32 v6, s49, v2
	v_lshl_add_u64 v[82:83], s[72:73], 0, v[2:3]
	v_mad_u32_u24 v7, v157, s64, v7
	v_and_b32_e32 v5, -16, v5
	v_mul_lo_u32 v10, v10, s64
	v_lshl_add_u32 v9, v9, 1, s49
	v_lshl_add_u64 v[84:85], s[82:83], 0, v[2:3]
	v_sub_u32_e32 v2, v157, v156
	s_add_i32 s24, s60, s67
	v_add_u32_e32 v88, 64, v2
	v_add_u32_e32 v89, s24, v5
	v_add_u32_e32 v87, v6, v4
	v_add_u32_e32 v159, v7, v8
	v_add_u32_e32 v158, v9, v10
	v_mov_b32_e32 v33, v155
	v_mov_b32_e32 v2, v155
	v_mov_b32_e32 v3, v155
	v_mov_b32_e32 v4, v155
	v_mov_b32_e32 v5, v155
	v_mov_b32_e32 v6, v155
	v_mov_b32_e32 v7, v155
	v_mov_b32_e32 v8, v155
	v_mov_b32_e32 v9, v155
	v_mov_b32_e32 v10, v155
	v_mov_b32_e32 v11, v155
	v_mov_b32_e32 v12, v155
	v_mov_b32_e32 v13, v155
	v_mov_b32_e32 v14, v155
	v_mov_b32_e32 v15, v155
	v_mov_b32_e32 v16, v155
	v_mov_b32_e32 v17, v155
	s_branch .LBB0_264
